# k10 + first four K fragment ds_reads of QK hoisted above the next-tile DMA issue block (compute segment leads with its reads in flight)
# baseline (speedup 1.0000x reference)
.LBB0_397:
	s_waitcnt vmcnt(0)
	s_add_i32 s96, s56, 1
	s_cmp_ge_i32 s96, s93
	s_waitcnt lgkmcnt(0)
	s_barrier
	ds_read_b128 v[128:131], v201 offset:0
	ds_read_b128 v[148:151], v201 offset:0x2000
	ds_read_b128 v[216:219], v203 offset:0
	ds_read_b128 v[220:223], v203 offset:0x2000
	s_cbranch_scc1 .LBB0_399
	s_lshl_b64 vcc, s[44:45], 8
	s_add_u32 s24, s54, vcc_lo
	s_addc_u32 s25, s55, vcc_hi
	s_add_u32 s14, s48, vcc_lo
	s_addc_u32 s15, s49, vcc_hi
	s_and_b32 s97, s96, 1
	s_mul_i32 s98, s97, 0xc000
	s_add_i32 s98, s98, s100
	s_add_i32 s99, s98, 0x8000
	s_mov_b32 m0, s99
	s_nop 0
	global_load_lds_dwordx4 v232, s[24:25]
	s_add_i32 m0, s99, 0x2000
	s_nop 0
	global_load_lds_dwordx4 v233, s[24:25]
	s_mov_b32 m0, s98
	s_nop 0
	global_load_lds_dwordx4 v234, s[14:15]
	s_add_i32 m0, s98, 0x2000
	s_nop 0
	global_load_lds_dwordx4 v235, s[14:15]
	s_add_u32 s24, s6, vcc_lo
	s_addc_u32 s25, s7, vcc_hi
	s_add_i32 m0, s98, 0x4000
	s_nop 0
	global_load_lds_dwordx4 v234, s[24:25]
	s_add_i32 m0, s98, 0x6000
	s_nop 0
	global_load_lds_dwordx4 v235, s[24:25]
.LBB0_399:
	s_cmp_ge_i32 s56, s94
	s_cbranch_scc1 .LBB0_405
	s_waitcnt lgkmcnt(2)
	s_nop 0
	v_mfma_f32_32x32x16_bf16 v[128:143], v[128:131], v[160:163], 0
	v_mfma_f32_32x32x16_bf16 v[144:159], v[148:151], v[160:163], 0
	ds_read_b128 v[224:227], v206 offset:0
	ds_read_b128 v[228:231], v206 offset:0x2000
	s_waitcnt lgkmcnt(2)
	v_mfma_f32_32x32x16_bf16 v[128:143], v[216:219], v[164:167], v[128:143]
	v_mfma_f32_32x32x16_bf16 v[144:159], v[220:223], v[164:167], v[144:159]
	ds_read_b128 v[216:219], v208 offset:0
	ds_read_b128 v[220:223], v208 offset:0x2000
	s_waitcnt lgkmcnt(2)
	v_mfma_f32_32x32x16_bf16 v[128:143], v[224:227], v[168:171], v[128:143]
	v_mfma_f32_32x32x16_bf16 v[144:159], v[228:231], v[168:171], v[144:159]
	ds_read_b128 v[224:227], v201 offset:0x80
	ds_read_b128 v[228:231], v201 offset:0x2080
	s_waitcnt lgkmcnt(2)
	v_mfma_f32_32x32x16_bf16 v[128:143], v[216:219], v[172:175], v[128:143]
	v_mfma_f32_32x32x16_bf16 v[144:159], v[220:223], v[172:175], v[144:159]
	ds_read_b128 v[216:219], v203 offset:0x80
	ds_read_b128 v[220:223], v203 offset:0x2080
	s_waitcnt lgkmcnt(2)
	v_mfma_f32_32x32x16_bf16 v[128:143], v[224:227], v[176:179], v[128:143]
	v_mfma_f32_32x32x16_bf16 v[144:159], v[228:231], v[176:179], v[144:159]
	ds_read_b128 v[224:227], v206 offset:0x80
	ds_read_b128 v[228:231], v206 offset:0x2080
	s_waitcnt lgkmcnt(2)
	v_mfma_f32_32x32x16_bf16 v[128:143], v[216:219], v[180:183], v[128:143]
	v_mfma_f32_32x32x16_bf16 v[144:159], v[220:223], v[180:183], v[144:159]
	ds_read_b128 v[216:219], v208 offset:0x80
	ds_read_b128 v[220:223], v208 offset:0x2080
	s_waitcnt lgkmcnt(2)
	v_mfma_f32_32x32x16_bf16 v[128:143], v[224:227], v[240:243], v[128:143]
	v_mfma_f32_32x32x16_bf16 v[144:159], v[228:231], v[240:243], v[144:159]
	s_waitcnt lgkmcnt(0)
	v_mfma_f32_32x32x16_bf16 v[128:143], v[216:219], v[244:247], v[128:143]
	s_cmp_eq_u32 s56, 0
	s_cselect_b64 vcc, -1, 0
	s_mov_b32 s14, 0x41000000
	v_mfma_f32_32x32x16_bf16 v[144:159], v[220:223], v[244:247], v[144:159]
	s_cbranch_scc1 .Ldiff_pad
	s_nop 7
	v_max_f32_e32 v215, v128, v129
	v_max3_f32 v215, v215, v130, v131
	v_max3_f32 v215, v215, v132, v133
	v_max3_f32 v215, v215, v134, v135
	v_max3_f32 v215, v215, v136, v137
	v_max3_f32 v215, v215, v138, v139
	v_max3_f32 v215, v215, v140, v141
	v_max3_f32 v215, v215, v142, v143
	v_max3_f32 v215, v215, v144, v145
	v_max3_f32 v215, v215, v146, v147
	v_max3_f32 v215, v215, v148, v149
	v_max3_f32 v215, v215, v150, v151
	v_max3_f32 v215, v215, v152, v153
	v_max3_f32 v215, v215, v154, v155
	v_max3_f32 v215, v215, v156, v157
	v_max3_f32 v215, v215, v158, v159
	s_branch .Ldiff_padjoin
